# speedup vs baseline: 1.0102x; 1.0033x over previous
; __device__ __forceinline__ float lo_bf(unsigned u) { return __uint_as_float(u << 16); }
; __device__ __forceinline__ float hi_bf(unsigned u) { return __uint_as_float(u & 0xffff0000u); }
; __device__ __forceinline__ int get_tid512() { int t = threadIdx.x; asm volatile("" : "+v"(t)); return t; }
; __device__ __forceinline__ void final_phase(const Params& p) {
;   const int tid_ = get_tid512(); const int lane = tid_ & 63, wave = tid_ >> 6;
;   for (int m = blockIdx.x * 8 + wave; m < TX; m += gridDim.x * 8) {
;     const u16* r = p.Rb + (size_t)m * 1024;
;     float v[16];
; #pragma unroll
;     for (int h = 0; h < 2; ++h) {
;       uint4 a = *(const uint4*)(r + h * 512 + lane * 8);
;       v[h * 8 + 0] = lo_bf(a.x); v[h * 8 + 1] = hi_bf(a.x); v[h * 8 + 2] = lo_bf(a.y); v[h * 8 + 3] = hi_bf(a.y);
;       v[h * 8 + 4] = lo_bf(a.z); v[h * 8 + 5] = hi_bf(a.z); v[h * 8 + 6] = lo_bf(a.w); v[h * 8 + 7] = hi_bf(a.w);
;     }
;     float ss = 0.f;
; #pragma unroll
;     for (int i = 0; i < 16; ++i) ss += v[i] * v[i];
; #pragma unroll
;     for (int o = 32; o >= 1; o >>= 1) ss += __shfl_xor(ss, o);
;     const float rstd = rsqrtf(ss * (1.f / 1024.f) + EPSV);
; #pragma unroll
;     for (int h = 0; h < 2; ++h) {
;       const int c = h * 512 + lane * 8;
; #pragma unroll
;       for (int q = 0; q < 2; ++q) {
;         float4 gg = *(const float4*)(p.norm_final + c + q * 4);
;         float4 o;
;         o.x = v[h * 8 + q * 4 + 0] * rstd * gg.x; o.y = v[h * 8 + q * 4 + 1] * rstd * gg.y;
;         o.z = v[h * 8 + q * 4 + 2] * rstd * gg.z; o.w = v[h * 8 + q * 4 + 3] * rstd * gg.w;
;         *(float4*)(p.OUT + (size_t)m * 1024 + c + q * 4) = o;
;       }
;     }
;   }
; }
.LBB0_1875:
	v_mov_b32_e32 v0, v206
	s_nop 0
	v_ashrrev_i32_e32 v2, 6, v0
	v_add_u32_e32 v2, s10, v2
	v_cmp_gt_i32_e32 vcc, s12, v2
	s_and_saveexec_b64 s[6:7], vcc
	s_cbranch_execz .LBB0_1874
	v_lshlrev_b32_e32 v0, 3, v0
	v_cmp_lt_i32_e32 vcc, v199, v198
	v_and_b32_e32 v3, 0x1f8, v0
	s_mov_b64 s[8:9], 0
	v_cndmask_b32_e32 v0, v197, v199, vcc
	v_cmp_lt_i32_e32 vcc, v200, v198
	v_lshlrev_b32_e32 v12, 2, v0
	s_nop 0
	v_cndmask_b32_e32 v0, v197, v200, vcc
	v_lshlrev_b32_e32 v13, 2, v0
	v_xor_b32_e32 v0, 8, v197
	v_cmp_lt_i32_e32 vcc, v0, v198
	s_nop 1
	v_cndmask_b32_e32 v0, v197, v0, vcc
	v_lshlrev_b32_e32 v14, 2, v0
	v_xor_b32_e32 v0, 4, v197
	v_cmp_lt_i32_e32 vcc, v0, v198
	s_nop 1
	v_cndmask_b32_e32 v0, v197, v0, vcc
	v_lshlrev_b32_e32 v15, 2, v0
	v_xor_b32_e32 v0, 2, v197
	v_cmp_lt_i32_e32 vcc, v0, v198
	s_nop 1
	v_cndmask_b32_e32 v0, v197, v0, vcc
	v_lshlrev_b32_e32 v16, 2, v0
	v_xor_b32_e32 v0, 1, v197
	v_cmp_lt_i32_e32 vcc, v0, v198
	s_nop 1
	v_cndmask_b32_e32 v0, v197, v0, vcc
	v_lshlrev_b32_e32 v17, 2, v0
	v_lshlrev_b32_e32 v0, 1, v3
	v_lshl_add_u64 v[4:5], s[0:1], 0, v[0:1]
	v_lshlrev_b32_e32 v0, 2, v3
	s_waitcnt lgkmcnt(0)
	v_lshl_add_u64 v[6:7], s[2:3], 0, v[0:1]
	v_lshl_add_u64 v[8:9], s[4:5], 0, v[0:1]
	global_load_dwordx4 v[60:63], v[6:7], off
	global_load_dwordx4 v[64:67], v[6:7], off offset:16
	global_load_dwordx4 v[68:71], v[6:7], off offset:2048
	global_load_dwordx4 v[72:75], v[6:7], off offset:2064
	s_waitcnt vmcnt(0)
.LBB0_1877:
	v_ashrrev_i32_e32 v3, 31, v2
	v_lshlrev_b64 v[18:19], 11, v[2:3]
	v_lshl_add_u64 v[30:31], v[4:5], 0, v[18:19]
	global_load_dwordx4 v[18:21], v[30:31], off
	global_load_dwordx4 v[22:25], v[30:31], off offset:1024
	v_mov_b32_e32 v26, v60
	v_mov_b32_e32 v27, v61
	v_mov_b32_e32 v28, v62
	v_mov_b32_e32 v29, v63
	s_waitcnt vmcnt(0)
	v_lshlrev_b32_e32 v30, 16, v18
	v_and_b32_e32 v31, 0xffff0000, v18
	v_lshlrev_b32_e32 v18, 16, v19
	v_and_b32_e32 v19, 0xffff0000, v19
	v_lshlrev_b32_e32 v32, 16, v20
	v_and_b32_e32 v33, 0xffff0000, v20
	v_lshlrev_b32_e32 v34, 16, v21
	v_and_b32_e32 v35, 0xffff0000, v21
	v_pk_mul_f32 v[20:21], v[30:31], v[30:31]
	v_pk_mul_f32 v[40:41], v[18:19], v[18:19]
	v_add_f32_e32 v0, v20, v21
	v_add_f32_e32 v0, v0, v40
	v_pk_mul_f32 v[42:43], v[32:33], v[32:33]
	v_add_f32_e32 v0, v41, v0
	v_add_f32_e32 v0, v42, v0
	v_pk_mul_f32 v[44:45], v[34:35], v[34:35]
	v_add_f32_e32 v0, v43, v0
	v_lshlrev_b32_e32 v36, 16, v22
	v_and_b32_e32 v37, 0xffff0000, v22
	v_add_f32_e32 v0, v44, v0
	v_pk_mul_f32 v[46:47], v[36:37], v[36:37]
	v_add_f32_e32 v0, v45, v0
	v_lshlrev_b32_e32 v22, 16, v23
	v_and_b32_e32 v23, 0xffff0000, v23
	v_add_f32_e32 v0, v46, v0
	v_pk_mul_f32 v[48:49], v[22:23], v[22:23]
	v_add_f32_e32 v0, v47, v0
	v_lshlrev_b32_e32 v38, 16, v24
	v_and_b32_e32 v39, 0xffff0000, v24
	v_add_f32_e32 v0, v48, v0
	v_pk_mul_f32 v[50:51], v[38:39], v[38:39]
	v_add_f32_e32 v0, v49, v0
	v_lshlrev_b32_e32 v24, 16, v25
	v_and_b32_e32 v25, 0xffff0000, v25
	v_add_f32_e32 v0, v50, v0
	v_pk_mul_f32 v[52:53], v[24:25], v[24:25]
	v_add_f32_e32 v0, v51, v0
	v_add_f32_e32 v0, v52, v0
	v_add_f32_e32 v0, v53, v0
	ds_bpermute_b32 v20, v12, v0
	s_waitcnt lgkmcnt(0)
	v_add_f32_e32 v0, v0, v20
	ds_bpermute_b32 v20, v13, v0
	s_waitcnt lgkmcnt(0)
	v_add_f32_e32 v0, v0, v20
	ds_bpermute_b32 v20, v14, v0
	s_waitcnt lgkmcnt(0)
	v_add_f32_e32 v0, v0, v20
	ds_bpermute_b32 v20, v15, v0
	s_waitcnt lgkmcnt(0)
	v_add_f32_e32 v0, v0, v20
	ds_bpermute_b32 v20, v16, v0
	s_waitcnt lgkmcnt(0)
	v_add_f32_e32 v0, v0, v20
	ds_bpermute_b32 v20, v17, v0
	s_waitcnt lgkmcnt(0)
	v_add_f32_e32 v0, v0, v20
	v_fmamk_f32 v0, v0, 0x3a800000, v11
	v_mul_f32_e32 v20, 0x4b800000, v0
	v_cmp_gt_f32_e32 vcc, s13, v0
	s_nop 1
	v_cndmask_b32_e32 v0, v0, v20, vcc
	v_rsq_f32_e32 v0, v0
	v_lshlrev_b64 v[20:21], 12, v[2:3]
	v_lshl_add_u64 v[40:41], v[8:9], 0, v[20:21]
	v_add_u32_e32 v2, s11, v2
	v_mul_f32_e32 v3, 0x45800000, v0
	v_cndmask_b32_e32 v0, v0, v3, vcc
	v_pk_mul_f32 v[20:21], v[0:1], v[30:31] op_sel_hi:[0,1]
	v_pk_mul_f32 v[30:31], v[0:1], v[18:19] op_sel_hi:[0,1]
	v_pk_mul_f32 v[18:19], v[26:27], v[20:21]
	v_pk_mul_f32 v[20:21], v[28:29], v[30:31]
	global_store_dwordx4 v[40:41], v[18:21], off
	s_nop 1
	v_mov_b32_e32 v18, v64
	v_mov_b32_e32 v19, v65
	v_mov_b32_e32 v20, v66
	v_mov_b32_e32 v21, v67
	v_pk_mul_f32 v[26:27], v[0:1], v[32:33] op_sel_hi:[0,1]
	v_pk_mul_f32 v[28:29], v[0:1], v[34:35] op_sel_hi:[0,1]
	v_pk_mul_f32 v[22:23], v[0:1], v[22:23] op_sel_hi:[0,1]
	v_cmp_lt_i32_e32 vcc, s14, v2
	v_pk_mul_f32 v[24:25], v[0:1], v[24:25] op_sel_hi:[0,1]
	s_or_b64 s[8:9], vcc, s[8:9]
	v_pk_mul_f32 v[18:19], v[18:19], v[26:27]
	v_pk_mul_f32 v[20:21], v[20:21], v[28:29]
	global_store_dwordx4 v[40:41], v[18:21], off offset:16
	s_nop 1
	v_mov_b32_e32 v18, v68
	v_mov_b32_e32 v19, v69
	v_mov_b32_e32 v20, v70
	v_mov_b32_e32 v21, v71
	v_pk_mul_f32 v[26:27], v[0:1], v[36:37] op_sel_hi:[0,1]
	v_pk_mul_f32 v[18:19], v[26:27], v[18:19]
	v_pk_mul_f32 v[20:21], v[22:23], v[20:21]
	global_store_dwordx4 v[40:41], v[18:21], off offset:2048
	s_nop 1
	v_mov_b32_e32 v18, v72
	v_mov_b32_e32 v19, v73
	v_mov_b32_e32 v20, v74
	v_mov_b32_e32 v21, v75
	v_pk_mul_f32 v[22:23], v[0:1], v[38:39] op_sel_hi:[0,1]
	v_pk_mul_f32 v[18:19], v[22:23], v[18:19]
	v_pk_mul_f32 v[20:21], v[24:25], v[20:21]
	global_store_dwordx4 v[40:41], v[18:21], off offset:2064
	s_andn2_b64 exec, exec, s[8:9]
	s_cbranch_execnz .LBB0_1877
	s_branch .LBB0_1874
